# in-proj feature-tile sweep reordered (branch-gate columns first, then descending) so the columns P2/P3 read first are the last written and still in Infinity Cache
# speedup vs baseline: 1.0872x; 1.0057x over previous
; #define REPS(k) for (int rp = 0; rp < ((PROBE == (k)) ? 2 : 1); ++rp)
; #define OPQ int tid = tid0; asm volatile("" : "+v"(tid));
; __global__ void __launch_bounds__(512) mega(Params p, int coop) {
;     ...
;   for (int g = 0; g < NGRP; ++g) {
;     for (int l = 0; l < DEPTH; ++l) {
;       const bool last = (l == DEPTH - 1);
;       REPS(10) {
;         for (int it = bid; it < TG / 8; it += nb) { OPQ norm_item(p, l, g, it, tid); }
;         GSYNC;
;       }
;       REPS(1) {
;         {
;           const int ntile = last ? 8 * 34 + 8 : 9 * 34;
;           auto tile_of = [&](int j, int& tl, int& tf) {
;             if (!last) { tl = j % 9; tf = j / 9; }
;             else if (j < 8 * 34) { tl = 1 + (j & 7); tf = j >> 3; }
;             else { tl = 0; const int q = j - 8 * 34; tf = q == 0 ? 1 : 4 + q; }
;           };
;           __syncthreads();
;           if (xr < ntile) {
;             OPQ
;             int tl, tf;
;             tile_of(xr, tl, tf);
;             gemm8_prefetch<1024>(p.WinT + ((long)l * NINP + tf * 256) * 1024, p.u + (long)(xx * 9 + tl) * 256 * 1024, smem, tid);
.LBB0_99:
	s_or_b64 exec, exec, s[2:3]
	s_and_b32 s10, s75, 7
	s_ashr_i32 s11, s75, 3
	s_ashr_i32 s77, s14, 3
	s_cmpk_lt_i32 s75, 0x900
	s_cselect_b64 s[2:3], -1, 0
	v_writelane_b32 v253, s2, 23
	s_barrier
	s_nop 0
	v_writelane_b32 v253, s3, 24
	s_mul_i32 s0, s15, s14
	v_readlane_b32 s8, v253, 0
	v_readlane_b32 s9, v253, 1
	s_load_dwordx16 s[80:95], s[8:9], 0xd0
	s_load_dword s1, s[8:9], 0x150
	s_mul_i32 s12, s10, 9
	s_load_dwordx16 s[40:55], s[8:9], 0x90
	v_mov_b32_e32 v157, 0
	v_mov_b32_e32 v196, 0x358637bd
	s_waitcnt lgkmcnt(0)
	s_mul_i32 s78, s0, s1
	s_add_u32 s0, s36, 0x200
	s_addc_u32 s1, s37, 0
	v_writelane_b32 v253, s0, 25
	v_bfrev_b32_e32 v252, 0.5
	s_movk_i32 s66, 0x900
	v_writelane_b32 v253, s1, 26
	s_add_u32 s0, s36, 0x1000
	s_addc_u32 s1, s37, 0
	v_writelane_b32 v253, s0, 27
	s_movk_i32 s72, 0x100
	s_movk_i32 s67, 0xff
	v_writelane_b32 v253, s1, 28
	s_add_u32 s0, s36, 0x1100
	s_addc_u32 s1, s37, 0
	v_writelane_b32 v253, s0, 29
	s_mov_b32 s68, 0x16000
	s_movk_i32 s69, 0x4000
	v_writelane_b32 v253, s1, 30
	s_add_u32 s0, s36, 0x1200
	s_addc_u32 s1, s37, 0
	v_writelane_b32 v253, s0, 31
	s_movk_i32 s70, 0x6000
	s_mov_b32 s73, 0x1a000
	v_writelane_b32 v253, s1, 32
	s_add_u32 s0, s36, 0x1300
	s_addc_u32 s1, s37, 0
	v_writelane_b32 v253, s0, 33
	s_cmp_eq_u32 s33, 15
	s_mov_b32 s65, 0x8000
	v_writelane_b32 v253, s1, 34
	s_cselect_b64 s[0:1], -1, 0
	v_writelane_b32 v253, s0, 35
	s_cmp_eq_u32 s33, 14
	s_mov_b32 s64, 0xa000
	v_writelane_b32 v253, s1, 36
	s_cselect_b64 s[0:1], -1, 0
	v_writelane_b32 v253, s0, 37
	s_cmp_eq_u32 s33, 13
	s_movk_i32 s71, 0x1000
	v_writelane_b32 v253, s1, 38
	s_cselect_b64 s[0:1], -1, 0
	v_writelane_b32 v253, s0, 39
	s_cmp_eq_u32 s33, 12
	s_movk_i32 s74, 0x90
	v_writelane_b32 v253, s1, 40
	s_cselect_b64 s[0:1], -1, 0
	v_writelane_b32 v253, s0, 41
	s_cmp_eq_u32 s33, 11
	s_mov_b32 s25, 0
	v_writelane_b32 v253, s1, 42
	s_cselect_b64 s[0:1], -1, 0
	v_writelane_b32 v253, s0, 43
	s_cmp_eq_u32 s33, 10
	s_mov_b64 s[26:27], 0x100
	v_writelane_b32 v253, s1, 44
	s_cselect_b64 s[0:1], -1, 0
	v_writelane_b32 v253, s0, 45
	s_cmp_eq_u32 s33, 9
	s_mov_b64 s[34:35], 0x80
	v_writelane_b32 v253, s1, 46
	s_cselect_b64 s[0:1], -1, 0
	v_writelane_b32 v253, s0, 47
	s_cmp_eq_u32 s33, 8
	s_mov_b64 s[28:29], 0x180
	v_writelane_b32 v253, s1, 48
	s_cselect_b64 s[0:1], -1, 0
	v_writelane_b32 v253, s0, 49
	s_cmp_eq_u32 s33, 7
	s_mov_b64 s[30:31], 0x40180
	v_writelane_b32 v253, s1, 50
	s_cselect_b64 s[0:1], -1, 0
	v_writelane_b32 v253, s0, 51
	s_cmp_eq_u32 s33, 6
	s_mov_b64 s[96:97], 0x1200000
	v_writelane_b32 v253, s1, 52
	s_cselect_b64 s[0:1], -1, 0
	v_writelane_b32 v253, s0, 53
	s_cmp_eq_u32 s33, 5
	s_mov_b32 s76, 0x3f803f80
	v_writelane_b32 v253, s1, 54
	s_cselect_b64 s[0:1], -1, 0
	v_writelane_b32 v253, s0, 55
	s_cmp_eq_u32 s33, 4
	s_nop 0
	v_writelane_b32 v253, s1, 56
	s_cselect_b64 s[0:1], -1, 0
	v_writelane_b32 v253, s0, 57
	s_cmp_eq_u32 s33, 3
	s_nop 0
	v_writelane_b32 v253, s1, 58
	s_cselect_b64 s[0:1], -1, 0
	v_writelane_b32 v253, s0, 59
	s_cmp_eq_u32 s33, 2
	s_nop 0
	v_writelane_b32 v253, s1, 60
	s_cselect_b64 s[0:1], -1, 0
	v_writelane_b32 v253, s0, 61
	s_cmp_eq_u32 s33, 1
	s_nop 0
	v_writelane_b32 v253, s1, 62
	s_cselect_b64 s[0:1], -1, 0
	v_writelane_b32 v253, s0, 63
	s_cmp_eq_u32 s33, 0
	s_nop 0
	v_writelane_b32 v254, s1, 0
	s_cselect_b64 s[0:1], -1, 0
	v_writelane_b32 v254, s0, 1
	s_nop 1
	v_writelane_b32 v254, s1, 2
	s_lshl_b32 s0, s33, 8
	s_add_u32 s0, s36, s0
	s_addc_u32 s1, s37, 0
	s_add_u32 s2, s0, 0x1400
	s_addc_u32 s3, s1, 0
	v_writelane_b32 v254, s2, 3
	s_add_u32 s0, s0, 0x2400
	s_addc_u32 s1, s1, 0
	v_writelane_b32 v254, s3, 4
	v_writelane_b32 v254, s0, 5
	s_movk_i32 s33, 0x4400
	s_nop 0
	v_writelane_b32 v254, s1, 6
	s_add_u32 s0, s36, 0x3400
	s_addc_u32 s1, s37, 0
	v_writelane_b32 v254, s0, 7
	s_nop 1
	v_writelane_b32 v254, s1, 8
	s_add_u32 s0, s36, 0x3500
	s_addc_u32 s1, s37, 0
	v_writelane_b32 v254, s0, 9
	s_nop 1
	v_writelane_b32 v254, s1, 10
	s_mul_hi_i32 s0, s11, 0x38e38e39
	s_ashr_i32 s1, s0, 1
	s_lshr_b32 s2, s0, 31
	s_add_i32 s1, s1, s2
	s_add_i32 s3, s1, 21
	v_writelane_b32 v254, s3, 11
	s_mul_i32 s1, s1, 9
	s_sub_i32 s1, s11, s1
	v_writelane_b32 v254, s1, 12
	s_add_i32 s1, s11, 0xfffffef4
	s_cmpk_lg_i32 s11, 0x110
	s_cselect_b32 s1, s1, 1
	s_ashr_i32 s0, s0, 3
	s_add_i32 s0, s0, s2
	s_lshl_b32 s2, s0, 3
	s_or_b32 s2, s2, s10
	s_mul_i32 s0, s0, 36
	s_mul_i32 s2, s2, 36
	s_sub_i32 s0, s11, s0
	s_add_i32 s5, s2, s0
	s_mul_hi_i32 s0, s5, 0x38e38e39
	s_lshr_b32 s2, s0, 31
	s_ashr_i32 s0, s0, 3
	s_add_i32 s0, s0, s2
	s_mul_i32 s2, s0, 36
	s_sub_i32 s2, s5, s2
	s_and_b32 s3, s11, 7
	v_writelane_b32 v254, s5, 13
	s_ashr_i32 s5, s0, 3
	s_lshl_b32 s2, s2, 6
	s_add_i32 s3, s3, 1
	s_ashr_i32 s4, s75, 6
	s_mul_hi_i32 s6, s5, 0x900
	s_mulk_i32 s5, 0x900
	s_ashr_i32 s7, s2, 31
	s_add_u32 s2, s5, s2
	s_addc_u32 s5, s6, s7
	s_mulk_i32 s5, 0x4400
	s_mul_hi_u32 s6, s2, 0x4400
	s_add_i32 s6, s6, s5
	s_mulk_i32 s2, 0x4400
	s_add_u32 s2, s88, s2
	s_addc_u32 s5, s89, s6
	s_lshl_b32 s0, s0, 7
; #define REPS(k) for (int rp = 0; rp < ((PROBE == (k)) ? 2 : 1); ++rp)
; #define OPQ int tid = tid0; asm volatile("" : "+v"(tid));
; __global__ void __launch_bounds__(512) mega(Params p, int coop) {
;     ...
;         {
;           OPQ
;           auto h1map = [&](int it) { const int hd = it & 7, t = it >> 3; return ((t / NSEG) * 8 + hd) * NSEG + t % NSEG; };
;           u16 kr[16];
;           hg_load_k(hg_zb(p, h1map(bid)), tid, kr);
;           for (int it = bid; it < 2304; it += nb) {
;             u16 kr2[16];
;             const int nxt = (it + nb < 2304) ? it + nb : it;
;             hg_load_k(hg_zb(p, h1map(nxt)), tid, kr2);
;             hg1_item(p, h1map(it), smem, tid, kr);
; #pragma unroll
;             for (int i = 0; i < 16; ++i) kr[i] = kr2[i];
;           }
;         }
;         for (int j = xr; j < 72 + 96 + 9; j += xper) {
;           OPQ
;           if (j < 72) { if (!(last && (j % 12) == 0)) qproj_item(p, l, xx * 12 + j % 12, j / 12, smem, tid); }
;           else if (j < 168) kvproj_item(p, l, xx * 12 + (j - 72) % 12, (j - 72) / 12, smem, tid);
;           else krope_item(p, xx * 9 + (j - 168), tid);
;         }
;         GSYNC;
;       }
;       REPS(3) {
;         for (int j = xr; j < (last ? 64 : 72); j += xper) {
;           OPQ
;           if (j < 64) attn_item(p, j >> 3, xx, NCTX + (j & 7) * 256, NTOK, smem, tid);
;           else attn_item(p, j - 64, xx, 0, NCTX, smem, tid);
;         }
;         if (!rp) {
;           const int r0 = last ? 0 : 8, nr = xper - r0;
;           if (nr > 0 && xr >= r0)
;             for (int k = xr - r0; k < 64; k += nr) { OPQ hg_combine_item(p, xx * 64 + k, tid); }
;           if (nr <= 0)
;             for (int it = bid; it < 512; it += nb) { OPQ hg_combine_item(p, it, tid); }
;         }
;         GSYNC;
;       }
;       REPS(4) {
;         {
;           OPQ
;           const int nh3 = last ? G * 8 * 32 : G * 8 * NSEG;
;           auto h3map = [&](int it) {
;             const int hd = it & 7, t = it >> 3;
;             return last ? ((t >> 5) * 8 + hd) * NSEG + 4 + (t & 31) : ((t / NSEG) * 8 + hd) * NSEG + t % NSEG;
;           };
;           u16 kr[16];
;           hg_load_k(hg_zb(p, h3map(bid)), tid, kr);
	s_and_b32 s0, s0, 0x380
	s_add_u32 s6, s2, s0
	s_addc_u32 s7, s5, 0
	v_writelane_b32 v254, s6, 14
	s_cmpk_lt_i32 s11, 0xb1
	s_nop 0
	v_writelane_b32 v254, s7, 15
	s_cselect_b64 s[6:7], -1, 0
	v_writelane_b32 v254, s6, 16
	s_add_i32 s0, s12, 0xffffff58
	s_lshl_b32 s2, s10, 16
	v_writelane_b32 v254, s7, 17
	v_writelane_b32 v254, s12, 18
	v_writelane_b32 v254, s0, 19
	s_lshl_b32 s0, s10, 6
	s_cmpk_gt_i32 s75, 0x1ff
	s_cselect_b64 s[6:7], -1, 0
	s_ashr_i32 s5, s75, 5
	s_and_b32 s5, s5, 0x3ffffff8
	v_writelane_b32 v254, s6, 20
	s_or_b32 s5, s5, s10
	s_mul_i32 s5, s5, 36
	v_writelane_b32 v254, s7, 21
	s_and_b32 s6, s11, 31
	s_add_i32 s5, s6, s5
	s_add_i32 s5, s5, 4
	s_cmpk_lt_i32 s11, 0x60
	v_writelane_b32 v254, s5, 22
	s_cselect_b64 s[6:7], -1, 0
	v_writelane_b32 v254, s6, 23
	s_cmp_lt_i32 s11, 64
	s_mul_i32 s5, s10, 0x900
	v_writelane_b32 v254, s7, 24
	s_cselect_b64 s[6:7], -1, 0
	v_writelane_b32 v254, s6, 25
	s_addk_i32 s5, 0x100
	s_mov_b32 s12, 0
	v_writelane_b32 v254, s7, 26
	v_writelane_b32 v254, s5, 27
	s_add_u32 s5, s52, 0x600000
	v_writelane_b32 v254, s5, 28
	s_addc_u32 s5, s53, 0
	s_cmpk_lt_i32 s75, 0x800
	v_writelane_b32 v254, s5, 29
	s_cselect_b64 s[6:7], -1, 0
	v_writelane_b32 v254, s6, 30
	s_cmpk_lt_i32 s11, 0x110
	s_cselect_b32 s1, s4, s1
	v_writelane_b32 v254, s7, 31
	v_writelane_b32 v254, s1, 32
	s_cselect_b32 s1, s3, 0
	s_add_u32 s4, s54, 0x18b000
	v_writelane_b32 v254, s1, 33
	s_addc_u32 s5, s55, 0
	v_writelane_b32 v254, s4, 34
	s_lshl_b32 s1, s75, 3
	s_lshl_b32 s24, s14, 3
	v_writelane_b32 v254, s5, 35
	s_add_u32 s4, s88, 60
	v_writelane_b32 v254, s1, 36
	s_addc_u32 s5, s89, 0
	v_writelane_b32 v254, s4, 37
	s_nop 1
	v_writelane_b32 v254, s5, 38
	s_add_u32 s4, s88, 0x100
	s_addc_u32 s5, s89, 0
	v_writelane_b32 v254, s4, 39
	s_nop 1
	v_writelane_b32 v254, s5, 40
	s_add_u32 s4, s46, 0x100
	s_addc_u32 s5, s47, 0
	v_writelane_b32 v254, s4, 41
	s_add_u32 s1, s94, 0x100
	s_nop 0
	v_writelane_b32 v254, s5, 42
	v_writelane_b32 v254, s1, 43
	s_addc_u32 s1, s95, 0
	v_writelane_b32 v254, s1, 44
	s_add_u32 s1, s92, 0x6000
	v_writelane_b32 v254, s1, 45
	s_addc_u32 s1, s93, 0
	v_writelane_b32 v254, s1, 46
	s_lshl_b32 s1, s11, 10
	s_add_i32 s1, s2, s1
	s_load_dwordx4 s[4:7], s[8:9], 0x110
	s_load_dwordx4 s[20:23], s[8:9], 0x128
	v_writelane_b32 v254, s1, 47
	s_lshl_b32 s1, s77, 10
	v_writelane_b32 v254, s1, 48
	s_lshl_b32 s1, s75, 10
	v_writelane_b32 v254, s1, 49
	s_lshl_b32 s1, s14, 10
	s_waitcnt lgkmcnt(0)
	s_add_u32 s2, s4, 0x100
	v_writelane_b32 v254, s1, 50
	s_addc_u32 s3, s5, 0
	v_writelane_b32 v254, s2, 51
	s_load_dwordx4 s[16:19], s[8:9], 0x68
	s_nop 0
	v_writelane_b32 v254, s3, 52
	s_add_u32 s2, s50, 0x100
	s_addc_u32 s3, s51, 0
	v_writelane_b32 v254, s2, 53
	s_lshl_b32 s1, s11, 8
	s_nop 0
	v_writelane_b32 v254, s3, 54
	v_writelane_b32 v254, s1, 55
	s_lshl_b32 s1, s77, 8
	v_writelane_b32 v254, s1, 56
	s_add_u32 s1, s50, 0x900100
	v_writelane_b32 v254, s1, 57
	s_addc_u32 s1, s51, 0
	v_writelane_b32 v254, s1, 58
	v_writelane_b32 v254, s11, 59
	s_lshl_b32 s1, s11, 4
	v_writelane_b32 v254, s1, 60
	s_lshl_b32 s1, s77, 4
	v_writelane_b32 v254, s1, 61
	s_add_u32 s2, s6, 0x100
	v_writelane_b32 v254, s4, 62
	s_addc_u32 s3, s7, 0
	s_nop 0
	v_writelane_b32 v255, s6, 0
	v_writelane_b32 v255, s7, 1
	v_writelane_b32 v255, s2, 2
	v_writelane_b32 v254, s5, 63
	s_mov_b64 s[4:5], 0x100000
	v_writelane_b32 v255, s3, 3
	s_add_u32 s2, s52, 0x100
	s_addc_u32 s3, s53, 0
	v_writelane_b32 v255, s2, 4
	s_add_u32 s1, s52, 0x600100
	v_writelane_b32 v253, s40, 7
	v_writelane_b32 v255, s3, 5
	v_writelane_b32 v255, s1, 6
	s_addc_u32 s1, s53, 0
	v_writelane_b32 v255, s1, 7
	s_lshl_b32 s0, s0, 1
	v_writelane_b32 v255, s0, 8
	v_writelane_b32 v255, s10, 9
	s_mul_i32 s0, s10, 12
	v_writelane_b32 v255, s0, 10
	s_load_dwordx2 s[0:1], s[8:9], 0x0
	v_writelane_b32 v253, s41, 8
	v_writelane_b32 v253, s42, 9
	v_writelane_b32 v253, s43, 10
	v_writelane_b32 v253, s44, 11
	s_waitcnt lgkmcnt(0)
	v_writelane_b32 v255, s0, 11
	v_writelane_b32 v253, s45, 12
	v_writelane_b32 v253, s46, 13
	v_writelane_b32 v255, s1, 12
	s_load_dwordx2 s[0:1], s[8:9], 0x10
	v_writelane_b32 v253, s47, 14
	v_writelane_b32 v253, s48, 15
	v_writelane_b32 v253, s49, 16
	v_writelane_b32 v253, s50, 17
	s_waitcnt lgkmcnt(0)
	v_writelane_b32 v255, s0, 13
	v_writelane_b32 v253, s51, 18
	v_writelane_b32 v253, s52, 19
	v_writelane_b32 v255, s1, 14
	s_load_dwordx2 s[0:1], s[8:9], 0x30
	v_writelane_b32 v253, s53, 20
	v_writelane_b32 v253, s54, 21
	v_writelane_b32 v253, s55, 22
	s_mov_b64 s[2:3], 0x40100
	s_waitcnt lgkmcnt(0)
	v_writelane_b32 v255, s0, 15
	s_nop 1
	v_writelane_b32 v255, s1, 16
	v_writelane_b32 v255, s16, 17
	s_mov_b64 s[0:1], 0x40080
	s_nop 0
	v_writelane_b32 v255, s17, 18
	v_writelane_b32 v255, s18, 19
	v_writelane_b32 v255, s19, 20
	v_writelane_b32 v255, s77, 21
	v_writelane_b32 v255, s20, 22
	s_nop 1
	v_writelane_b32 v255, s21, 23
	v_writelane_b32 v255, s22, 24
	v_writelane_b32 v255, s23, 25
	v_writelane_b32 v255, s78, 26
	v_writelane_b32 v255, s24, 27
	s_branch .LBB0_101

; #define OPQ int tid = tid0; asm volatile("" : "+v"(tid));
; __global__ void __launch_bounds__(512) mega(Params p, int coop) {
;     ...
;           auto tile_of = [&](int j, int& tl, int& tf) {
;             if (!last) { tl = j % 9; tf = j / 9; }
;             else if (j < 8 * 34) { tl = 1 + (j & 7); tf = j >> 3; }
;             else { tl = 0; const int q = j - 8 * 34; tf = q == 0 ? 1 : 4 + q; }
;           };
;           __syncthreads();
;           if (xr < ntile) {
;             OPQ
;             int tl, tf;
;             tile_of(xr, tl, tf);
;             gemm8_prefetch<1024>(p.WinT + ((long)l * NINP + tf * 256) * 1024, p.u + (long)(xx * 9 + tl) * 256 * 1024, smem, tid);
;           }
;           for (int j = xr; j < ntile; j += xper) {
;             OPQ
;             int tl, tf, ntl = 0, ntf = 0;
;             tile_of(j, tl, tf);
.LBB0_167:
	v_readlane_b32 s6, v255, 40
	v_readlane_b32 s7, v255, 41
	v_mov_b32_e32 v148, v197
	s_andn2_b64 vcc, exec, s[6:7]
	v_cndmask_b32_e64 v0, 0, 1, s[6:7]
	v_cmp_ne_u32_e64 s[38:39], 1, v0
	s_mov_b64 s[6:7], -1
	s_cbranch_vccnz .LBB0_169
	s_mul_hi_i32 s6, s19, 0x38e38e39
	s_lshr_b32 s7, s6, 31
	s_ashr_i32 s6, s6, 1
	s_add_i32 s10, s6, s7
	s_mul_i32 s6, s10, 9
	s_sub_i32 s11, s19, s6
	s_add_i32 s6, s10, 21
	s_sub_i32 s7, 33, s10
	s_cmp_lt_i32 s10, 13
	s_cselect_b32 s10, s6, s7
	s_mov_b64 s[6:7], 0

; #define OPQ int tid = tid0; asm volatile("" : "+v"(tid));
; __global__ void __launch_bounds__(512) mega(Params p, int coop) {
;     ...
;           for (int j = xr; j < ntile; j += xper) {
;             OPQ
;             int tl, tf, ntl = 0, ntf = 0;
;             tile_of(j, tl, tf);
;             const int jn = j + xper;
;             const bool hn = jn < ntile;
;             if (hn) tile_of(jn, ntl, ntf);
;             inproj_item(p, l, xx * 9 + tl, tf, hn ? xx * 9 + ntl : -1, ntf, smem, tid);
.LBB0_174:
	s_add_i32 s19, s19, s77
	s_cmp_lt_i32 s19, s15
	s_cselect_b64 s[8:9], -1, 0
	s_cmp_ge_i32 s19, s15
	s_cselect_b64 s[42:43], -1, 0
	s_mov_b32 s24, 0
	s_and_b64 vcc, exec, s[42:43]
	s_mov_b32 s46, 0
	s_cbranch_vccnz .LBB0_182
	s_and_b64 vcc, exec, s[38:39]
	s_mov_b64 s[6:7], -1
	s_cbranch_vccnz .LBB0_177
	s_mul_hi_i32 s6, s19, 0x38e38e39
	s_lshr_b32 s7, s6, 31
	s_ashr_i32 s6, s6, 1
	s_add_i32 s46, s6, s7
	s_mul_i32 s6, s46, 9
	s_sub_i32 s24, s19, s6
	s_add_i32 s6, s46, 21
	s_sub_i32 s7, 33, s46
	s_cmp_lt_i32 s46, 13
	s_cselect_b32 s46, s6, s7
	s_mov_b64 s[6:7], 0
